# attention key loop: one static s_setprio 1 for waves 4-7 (map 1) for the whole loop, no per-segment toggles
# baseline (speedup 1.0000x reference)
; #define AT_LOADK(kt) do { _Pragma("unroll") for (int i_ = 0; i_ < 2; ++i_) { const int id_ = tid + 512 * i_; \
;             kr[i_] = *(const u32x4*)(kbase + (size_t)((kt) * 64 + (id_ >> 4)) * 4096 + (id_ & 15) * 8); } } while (0)
; #define AT_LOADV(kt) do { _Pragma("unroll") for (int i_ = 0; i_ < 2; ++i_) { const int id_ = tid + 512 * i_; \
;             vr[i_] = *(const u32x4*)(vbase + (size_t)(id_ >> 3) * 4096 + (kt) * 64 + (id_ & 7) * 8); } } while (0)
; __device__ __forceinline__ void phase_attn(const Params& p, unsigned char* lds) {
;     ...
;         for (int kt = 0; kt < 64; ++kt) {
;             const int buf = kt & 1;
;             if (kt + 1 < 64) { AT_LOADK((kt + 1 + toff) & 63); AT_LOADV((kt + 1 + toff) & 63); }
;             AT_QK(st, buf);
.LBB0_2021:
	s_cmp_lg_u64 s[4:5], 0
	s_cbranch_scc0 .Lat_noprio
	s_setprio 1

; #define AT_STOREK(buf) do { _Pragma("unroll") for (int i_ = 0; i_ < 2; ++i_) { const int id_ = tid + 512 * i_; \
;             *(u32x4*)(sKt + (buf) * 8704 + (id_ >> 4) * 136 + (id_ & 15) * 8) = kr[i_]; } } while (0)
; #define AT_STOREV(buf) do { _Pragma("unroll") for (int i_ = 0; i_ < 2; ++i_) { const int id_ = tid + 512 * i_; \
;             *(u32x4*)(sVt + (buf) * 9216 + (id_ >> 3) * 72 + (id_ & 7) * 8) = vr[i_]; } } while (0)
; #define AT_LDV(set, vb) do { _Pragma("unroll") for (int kb = 0; kb < 2; ++kb) _Pragma("unroll") for (int s2 = 0; s2 < 2; ++s2) \
;                     vf[set][kb * 2 + s2] = *(const bf16x8*)(sVt + buf * 9216 + (32 * (vb) + ql) * 72 + 32 * kb + 16 * s2 + 8 * g); } while (0)
; __device__ __forceinline__ void phase_attn(const Params& p, unsigned char* lds) {
;     ...
;                 AT_LDV(0, 0);
; #pragma unroll
;                 for (int vb = 0; vb < 4; ++vb) {
;                     if (vb < 3) AT_LDV((vb + 1) & 1, vb + 1);
;                     __builtin_amdgcn_sched_barrier(0);
;                     __builtin_amdgcn_s_setprio(2);
; #pragma unroll
;                     for (int kb = 0; kb < 2; ++kb)
; #pragma unroll
;                         for (int s2 = 0; s2 < 2; ++s2) ot[vb] = __builtin_amdgcn_mfma_f32_32x32x16_bf16(vf[vb & 1][kb * 2 + s2], P[kb][s2], ot[vb], 0, 0, 0);
;                     __builtin_amdgcn_s_setprio(0);
;                     __builtin_amdgcn_sched_barrier(0);
;                 }
;     ...
;             }
;             if (kt + 1 < 64) { AT_STOREK(buf ^ 1); AT_STOREV(buf ^ 1); }
;             __syncthreads();
;         }
;     ...
;         lsum += __shfl_xor(lsum, 32);
;         const float inv = 1.0f / lsum;
;         if (cmap == 1) {
; #pragma unroll
;             for (int vb = 0; vb < 4; ++vb)
; #pragma unroll
;                 for (int i = 0; i < 16; ++i) ex[(vb * 16 + i) * 256 + qsub * 64 + lane] = ot[vb][i] * inv;
.Lat_norescale_10:
	ds_read_b128 v[172:175], v147 offset:34816
	ds_read_b128 v[176:179], v147 offset:34848
	ds_read_b128 v[180:183], v147 offset:34880
	ds_read_b128 v[184:187], v147 offset:34912
	ds_read_b128 v[188:191], v147 offset:39424
	ds_read_b128 v[192:195], v147 offset:39456
	ds_read_b128 v[228:231], v147 offset:39488
	ds_read_b128 v[232:235], v147 offset:39520
	v_add_f32_e32 v128, v128, v236
	s_waitcnt lgkmcnt(7)
	v_mfma_f32_32x32x16_bf16 v[48:63], v[172:175], v[196:199], v[48:63]
	s_waitcnt lgkmcnt(6)
	v_mfma_f32_32x32x16_bf16 v[48:63], v[176:179], v[200:203], v[48:63]
	s_waitcnt lgkmcnt(5)
	v_mfma_f32_32x32x16_bf16 v[48:63], v[180:183], v[212:215], v[48:63]
	s_waitcnt lgkmcnt(4)
	v_mfma_f32_32x32x16_bf16 v[48:63], v[184:187], v[216:219], v[48:63]
	ds_read_b128 v[172:175], v147 offset:44032
	ds_read_b128 v[176:179], v147 offset:44064
	ds_read_b128 v[180:183], v147 offset:44096
	ds_read_b128 v[184:187], v147 offset:44128
	s_waitcnt lgkmcnt(7)
	v_mfma_f32_32x32x16_bf16 v[32:47], v[188:191], v[196:199], v[32:47]
	s_waitcnt lgkmcnt(6)
	v_mfma_f32_32x32x16_bf16 v[32:47], v[192:195], v[200:203], v[32:47]
	s_waitcnt lgkmcnt(5)
	v_mfma_f32_32x32x16_bf16 v[32:47], v[228:231], v[212:215], v[32:47]
	s_waitcnt lgkmcnt(4)
	v_mfma_f32_32x32x16_bf16 v[32:47], v[232:235], v[216:219], v[32:47]
	ds_read_b128 v[188:191], v147 offset:48640
	ds_read_b128 v[192:195], v147 offset:48672
	ds_read_b128 v[228:231], v147 offset:48704
	ds_read_b128 v[232:235], v147 offset:48736
	s_waitcnt lgkmcnt(7)
	v_mfma_f32_32x32x16_bf16 v[16:31], v[172:175], v[196:199], v[16:31]
	s_waitcnt lgkmcnt(6)
	v_mfma_f32_32x32x16_bf16 v[16:31], v[176:179], v[200:203], v[16:31]
	s_waitcnt lgkmcnt(5)
	v_mfma_f32_32x32x16_bf16 v[16:31], v[180:183], v[212:215], v[16:31]
	s_waitcnt lgkmcnt(4)
	v_mfma_f32_32x32x16_bf16 v[16:31], v[184:187], v[216:219], v[16:31]
	s_waitcnt lgkmcnt(3)
	v_mfma_f32_32x32x16_bf16 v[0:15], v[188:191], v[196:199], v[0:15]
	s_waitcnt lgkmcnt(2)
	v_mfma_f32_32x32x16_bf16 v[0:15], v[192:195], v[200:203], v[0:15]
	s_waitcnt lgkmcnt(1)
	v_mfma_f32_32x32x16_bf16 v[0:15], v[228:231], v[212:215], v[0:15]
	s_waitcnt lgkmcnt(0)
	v_mfma_f32_32x32x16_bf16 v[0:15], v[232:235], v[216:219], v[0:15]
	s_setprio 0
	v_mov_b32_e32 v64, v128
	ds_bpermute_b32 v65, v158, v64
	s_waitcnt lgkmcnt(0)
	s_barrier
	v_add_f32_e32 v64, v64, v65
	v_rcp_f32_e32 v66, v64
	s_nop 0
	v_fma_f32 v68, -v64, v66, 1.0
	v_fma_f32 v65, v68, v66, v66
	v_div_fixup_f32 v64, v65, v64, 1.0
	s_and_saveexec_b64 s[20:21], s[4:5]
	s_cbranch_execz .LBB0_2029
	v_mul_f32_e32 v65, v48, v64
	v_mul_f32_e32 v66, v49, v64
	ds_write2st64_b32 v160, v65, v66 offset1:4
	v_mul_f32_e32 v65, v50, v64
	v_mul_f32_e32 v66, v51, v64
	ds_write2st64_b32 v160, v65, v66 offset0:8 offset1:12
	v_mul_f32_e32 v65, v52, v64
	v_mul_f32_e32 v66, v53, v64
	ds_write2st64_b32 v160, v65, v66 offset0:16 offset1:20
	v_mul_f32_e32 v65, v54, v64
	v_mul_f32_e32 v66, v55, v64
	ds_write2st64_b32 v160, v65, v66 offset0:24 offset1:28
	v_mul_f32_e32 v65, v56, v64
	v_mul_f32_e32 v66, v57, v64
	ds_write2st64_b32 v160, v65, v66 offset0:32 offset1:36
	v_mul_f32_e32 v65, v58, v64
	v_mul_f32_e32 v66, v59, v64
	ds_write2st64_b32 v160, v65, v66 offset0:40 offset1:44
	v_mul_f32_e32 v65, v60, v64
	v_mul_f32_e32 v66, v61, v64
	ds_write2st64_b32 v160, v65, v66 offset0:48 offset1:52
	v_mul_f32_e32 v65, v62, v64
	v_mul_f32_e32 v66, v63, v64
	ds_write2st64_b32 v160, v65, v66 offset0:56 offset1:60
	v_mul_f32_e32 v65, v32, v64
	v_mul_f32_e32 v66, v33, v64
	ds_write2st64_b32 v160, v65, v66 offset0:64 offset1:68
	v_mul_f32_e32 v65, v34, v64
	v_mul_f32_e32 v66, v35, v64
	ds_write2st64_b32 v160, v65, v66 offset0:72 offset1:76
	v_mul_f32_e32 v65, v36, v64
	v_mul_f32_e32 v66, v37, v64
	ds_write2st64_b32 v160, v65, v66 offset0:80 offset1:84
	v_mul_f32_e32 v65, v38, v64
	v_mul_f32_e32 v66, v39, v64
	ds_write2st64_b32 v160, v65, v66 offset0:88 offset1:92
	v_mul_f32_e32 v65, v40, v64
	v_mul_f32_e32 v66, v41, v64
	ds_write2st64_b32 v160, v65, v66 offset0:96 offset1:100
	v_mul_f32_e32 v65, v42, v64
	v_mul_f32_e32 v66, v43, v64
	ds_write2st64_b32 v160, v65, v66 offset0:104 offset1:108
	v_mul_f32_e32 v65, v44, v64
	v_mul_f32_e32 v66, v45, v64
	ds_write2st64_b32 v160, v65, v66 offset0:112 offset1:116
	v_mul_f32_e32 v65, v46, v64
	v_mul_f32_e32 v66, v47, v64
	ds_write2st64_b32 v160, v65, v66 offset0:120 offset1:124
	v_mul_f32_e32 v65, v16, v64
	v_mul_f32_e32 v66, v17, v64
	ds_write2st64_b32 v160, v65, v66 offset0:128 offset1:132
	v_mul_f32_e32 v65, v18, v64
	v_mul_f32_e32 v66, v19, v64
	ds_write2st64_b32 v160, v65, v66 offset0:136 offset1:140
	v_mul_f32_e32 v65, v20, v64
	v_mul_f32_e32 v66, v21, v64
	ds_write2st64_b32 v160, v65, v66 offset0:144 offset1:148
	v_mul_f32_e32 v65, v22, v64
	v_mul_f32_e32 v66, v23, v64
	ds_write2st64_b32 v160, v65, v66 offset0:152 offset1:156
	v_mul_f32_e32 v65, v24, v64
	v_mul_f32_e32 v66, v25, v64
	ds_write2st64_b32 v160, v65, v66 offset0:160 offset1:164
	v_mul_f32_e32 v65, v26, v64
	v_mul_f32_e32 v66, v27, v64
	ds_write2st64_b32 v160, v65, v66 offset0:168 offset1:172
	v_mul_f32_e32 v65, v28, v64
	v_mul_f32_e32 v66, v29, v64
	ds_write2st64_b32 v160, v65, v66 offset0:176 offset1:180
	v_mul_f32_e32 v65, v30, v64
	v_mul_f32_e32 v66, v31, v64
	ds_write2st64_b32 v160, v65, v66 offset0:184 offset1:188
	v_mul_f32_e32 v65, v0, v64
	v_mul_f32_e32 v66, v1, v64
	ds_write2st64_b32 v160, v65, v66 offset0:192 offset1:196
	v_mul_f32_e32 v65, v2, v64
	v_mul_f32_e32 v66, v3, v64
	ds_write2st64_b32 v160, v65, v66 offset0:200 offset1:204
	v_mul_f32_e32 v65, v4, v64
	v_mul_f32_e32 v66, v5, v64
	ds_write2st64_b32 v160, v65, v66 offset0:208 offset1:212
	v_mul_f32_e32 v65, v6, v64
	v_mul_f32_e32 v66, v7, v64
	ds_write2st64_b32 v160, v65, v66 offset0:216 offset1:220
	v_mul_f32_e32 v65, v8, v64
	v_mul_f32_e32 v66, v9, v64
	ds_write2st64_b32 v160, v65, v66 offset0:224 offset1:228
	v_mul_f32_e32 v65, v10, v64
	v_mul_f32_e32 v66, v11, v64
	ds_write2st64_b32 v160, v65, v66 offset0:232 offset1:236
	v_mul_f32_e32 v65, v12, v64
	v_mul_f32_e32 v66, v13, v64
	ds_write2st64_b32 v160, v65, v66 offset0:240 offset1:244
	v_mul_f32_e32 v65, v14, v64
	v_mul_f32_e32 v66, v15, v64
	ds_write2st64_b32 v160, v65, v66 offset0:248 offset1:252
